# v88 + toppoll: grid-barrier XCD leaders poll the cross-XCD arrival counter (TOP >= target) instead of the generation word bumped one round trip later
# speedup vs baseline: 1.0164x; 1.0028x over previous
.LBB0_765:
	s_or_b64 exec, exec, s[18:19]
	s_waitcnt vmcnt(0)
	v_readfirstlane_b32 s7, v4
	v_cvt_f32_u32_e32 v4, v2
	v_sub_u32_e32 v5, 0, v2
	v_add_u32_e32 v3, s7, v3
	v_readlane_b32 s8, v255, 10
	v_rcp_iflag_f32_e32 v4, v4
	v_readlane_b32 s9, v255, 11
	s_mov_b64 s[18:19], -1
	v_mul_f32_e32 v4, 0x4f7ffffe, v4
	v_cvt_u32_f32_e32 v4, v4
	v_mul_lo_u32 v5, v5, v4
	v_mul_hi_u32 v5, v4, v5
	v_add_u32_e32 v4, v4, v5
	v_mul_hi_u32 v4, v3, v4
	v_mul_lo_u32 v5, v4, v2
	v_sub_u32_e32 v5, v3, v5
	v_cmp_ge_u32_e32 vcc, v5, v2
	v_add_u32_e32 v6, 1, v4
	v_add_u32_e32 v3, 1, v3
	v_cndmask_b32_e32 v4, v4, v6, vcc
	v_sub_u32_e32 v6, v5, v2
	v_cndmask_b32_e32 v5, v5, v6, vcc
	v_cmp_ge_u32_e32 vcc, v5, v2
	v_add_u32_e32 v5, 1, v4
	s_nop 0
	v_cndmask_b32_e32 v4, v4, v5, vcc
	v_mul_lo_u32 v5, v2, v4
	v_add_u32_e32 v2, v5, v2
	v_cmp_ne_u32_e32 vcc, v3, v2
	v_mov_b32_e32 v6, v2
	v_mov_b64_e32 v[2:3], s[8:9]
	s_and_saveexec_b64 s[14:15], vcc
	s_cbranch_execz .LBB0_777
	v_readlane_b32 s8, v255, 8
	v_readlane_b32 s9, v255, 9
	s_mov_b64 s[22:23], 0
	s_nop 3
	global_load_dword v2, v181, s[8:9] sc1
	s_waitcnt vmcnt(0)
	v_cmp_lt_u32_e32 vcc, v2, v6
	s_and_saveexec_b64 s[18:19], vcc
	s_cbranch_execz .LBB0_776
	s_mov_b32 s7, 1
	s_branch .LBB0_769

.LBB0_771:
	v_readlane_b32 s8, v255, 8
	v_readlane_b32 s9, v255, 9
	s_add_i32 s7, s7, 1
	s_mov_b64 s[28:29], -1
	s_nop 2
	global_load_dword v2, v181, s[8:9] sc1
	s_waitcnt vmcnt(0)
	v_cmp_ge_u32_e32 vcc, v2, v6
	s_orn2_b64 s[26:27], vcc, exec
	s_branch .LBB0_768

.LBB0_980:
	s_or_b64 exec, exec, s[18:19]
	s_waitcnt vmcnt(0)
	v_readfirstlane_b32 s6, v4
	v_cvt_f32_u32_e32 v4, v2
	v_sub_u32_e32 v5, 0, v2
	v_add_u32_e32 v3, s6, v3
	v_readlane_b32 s6, v255, 10
	v_rcp_iflag_f32_e32 v4, v4
	v_readlane_b32 s7, v255, 11
	s_mov_b64 s[18:19], -1
	v_mul_f32_e32 v4, 0x4f7ffffe, v4
	v_cvt_u32_f32_e32 v4, v4
	v_mul_lo_u32 v5, v5, v4
	v_mul_hi_u32 v5, v4, v5
	v_add_u32_e32 v4, v4, v5
	v_mul_hi_u32 v4, v3, v4
	v_mul_lo_u32 v5, v4, v2
	v_sub_u32_e32 v5, v3, v5
	v_cmp_ge_u32_e32 vcc, v5, v2
	v_add_u32_e32 v6, 1, v4
	v_add_u32_e32 v3, 1, v3
	v_cndmask_b32_e32 v4, v4, v6, vcc
	v_sub_u32_e32 v6, v5, v2
	v_cndmask_b32_e32 v5, v5, v6, vcc
	v_cmp_ge_u32_e32 vcc, v5, v2
	v_add_u32_e32 v5, 1, v4
	s_nop 0
	v_cndmask_b32_e32 v4, v4, v5, vcc
	v_mul_lo_u32 v5, v2, v4
	v_add_u32_e32 v2, v5, v2
	v_cmp_ne_u32_e32 vcc, v3, v2
	v_mov_b32_e32 v6, v2
	v_mov_b64_e32 v[2:3], s[6:7]
	s_and_saveexec_b64 s[14:15], vcc
	s_cbranch_execz .LBB0_992
	v_readlane_b32 s6, v255, 8
	v_readlane_b32 s7, v255, 9
	s_mov_b64 s[22:23], 0
	s_nop 3
	global_load_dword v2, v181, s[6:7] sc1
	s_waitcnt vmcnt(0)
	v_cmp_lt_u32_e32 vcc, v2, v6
	s_and_saveexec_b64 s[18:19], vcc
	s_cbranch_execz .LBB0_991
	s_mov_b32 s6, 1
	s_branch .LBB0_984

.LBB0_986:
	v_readlane_b32 s8, v255, 8
	v_readlane_b32 s9, v255, 9
	s_add_i32 s6, s6, 1
	s_mov_b64 s[28:29], -1
	s_nop 2
	global_load_dword v2, v181, s[8:9] sc1
	s_waitcnt vmcnt(0)
	v_cmp_ge_u32_e32 vcc, v2, v6
	s_orn2_b64 s[26:27], vcc, exec
	s_branch .LBB0_983

.LBB0_1389:
	s_or_b64 exec, exec, s[22:23]
	s_waitcnt vmcnt(0)
	v_readfirstlane_b32 s7, v4
	v_cvt_f32_u32_e32 v4, v2
	v_sub_u32_e32 v5, 0, v2
	v_add_u32_e32 v3, s7, v3
	v_readlane_b32 s8, v255, 10
	v_rcp_iflag_f32_e32 v4, v4
	v_readlane_b32 s9, v255, 11
	s_mov_b64 s[22:23], -1
	v_mul_f32_e32 v4, 0x4f7ffffe, v4
	v_cvt_u32_f32_e32 v4, v4
	v_mul_lo_u32 v5, v5, v4
	v_mul_hi_u32 v5, v4, v5
	v_add_u32_e32 v4, v4, v5
	v_mul_hi_u32 v4, v3, v4
	v_mul_lo_u32 v5, v4, v2
	v_sub_u32_e32 v5, v3, v5
	v_cmp_ge_u32_e32 vcc, v5, v2
	v_add_u32_e32 v6, 1, v4
	v_add_u32_e32 v3, 1, v3
	v_cndmask_b32_e32 v4, v4, v6, vcc
	v_sub_u32_e32 v6, v5, v2
	v_cndmask_b32_e32 v5, v5, v6, vcc
	v_cmp_ge_u32_e32 vcc, v5, v2
	v_add_u32_e32 v5, 1, v4
	s_nop 0
	v_cndmask_b32_e32 v4, v4, v5, vcc
	v_mul_lo_u32 v5, v2, v4
	v_add_u32_e32 v2, v5, v2
	v_cmp_ne_u32_e32 vcc, v3, v2
	v_mov_b32_e32 v6, v2
	v_mov_b64_e32 v[2:3], s[8:9]
	s_and_saveexec_b64 s[18:19], vcc
	s_cbranch_execz .LBB0_1401
	v_readlane_b32 s8, v255, 8
	v_readlane_b32 s9, v255, 9
	s_mov_b64 s[24:25], 0
	s_nop 3
	global_load_dword v2, v181, s[8:9] sc1
	s_waitcnt vmcnt(0)
	v_cmp_lt_u32_e32 vcc, v2, v6
	s_and_saveexec_b64 s[22:23], vcc
	s_cbranch_execz .LBB0_1400
	s_mov_b32 s7, 1
	s_branch .LBB0_1393

.LBB0_1395:
	v_readlane_b32 s8, v255, 8
	v_readlane_b32 s9, v255, 9
	s_add_i32 s7, s7, 1
	s_mov_b64 s[30:31], -1
	s_nop 2
	global_load_dword v2, v181, s[8:9] sc1
	s_waitcnt vmcnt(0)
	v_cmp_ge_u32_e32 vcc, v2, v6
	s_orn2_b64 s[28:29], vcc, exec
	s_branch .LBB0_1392

.LBB0_1534:
	s_or_b64 exec, exec, s[14:15]
	s_waitcnt vmcnt(0)
	v_readfirstlane_b32 s6, v4
	v_cvt_f32_u32_e32 v4, v2
	v_sub_u32_e32 v5, 0, v2
	v_add_u32_e32 v3, s6, v3
	v_readlane_b32 s6, v255, 10
	v_rcp_iflag_f32_e32 v4, v4
	v_readlane_b32 s7, v255, 11
	s_mov_b64 s[14:15], -1
	v_mul_f32_e32 v4, 0x4f7ffffe, v4
	v_cvt_u32_f32_e32 v4, v4
	v_mul_lo_u32 v5, v5, v4
	v_mul_hi_u32 v5, v4, v5
	v_add_u32_e32 v4, v4, v5
	v_mul_hi_u32 v4, v3, v4
	v_mul_lo_u32 v5, v4, v2
	v_sub_u32_e32 v5, v3, v5
	v_cmp_ge_u32_e32 vcc, v5, v2
	v_add_u32_e32 v6, 1, v4
	v_add_u32_e32 v3, 1, v3
	v_cndmask_b32_e32 v4, v4, v6, vcc
	v_sub_u32_e32 v6, v5, v2
	v_cndmask_b32_e32 v5, v5, v6, vcc
	v_cmp_ge_u32_e32 vcc, v5, v2
	v_add_u32_e32 v5, 1, v4
	s_nop 0
	v_cndmask_b32_e32 v4, v4, v5, vcc
	v_mul_lo_u32 v5, v2, v4
	v_add_u32_e32 v2, v5, v2
	v_cmp_ne_u32_e32 vcc, v3, v2
	v_mov_b32_e32 v6, v2
	v_mov_b64_e32 v[2:3], s[6:7]
	s_and_saveexec_b64 s[10:11], vcc
	s_cbranch_execz .LBB0_1546
	v_readlane_b32 s6, v255, 8
	v_readlane_b32 s7, v255, 9
	s_mov_b64 s[18:19], 0
	s_nop 3
	global_load_dword v2, v181, s[6:7] sc1
	s_waitcnt vmcnt(0)
	v_cmp_lt_u32_e32 vcc, v2, v6
	s_and_saveexec_b64 s[14:15], vcc
	s_cbranch_execz .LBB0_1545
	s_mov_b32 s6, 1
	s_branch .LBB0_1538

.LBB0_1540:
	v_readlane_b32 s8, v255, 8
	v_readlane_b32 s9, v255, 9
	s_add_i32 s6, s6, 1
	s_mov_b64 s[26:27], -1
	s_nop 2
	global_load_dword v2, v181, s[8:9] sc1
	s_waitcnt vmcnt(0)
	v_cmp_ge_u32_e32 vcc, v2, v6
	s_orn2_b64 s[24:25], vcc, exec
	s_branch .LBB0_1537
